# phase 5: PLE tiles stream the DMA ring across tile boundaries (next tile A0/B0/A1 requested in the last two K stages, tile head without DMA); half-tile x loads issued in K stage 14
# baseline (speedup 1.0000x reference)
.LBB0_884:
	s_lshl_b32 s5, s59, 6
	s_lshl_b32 s4, s12, 7
	s_and_b32 s5, s5, 64
	s_or_b32 s4, s4, s5
	s_ashr_i32 s5, s4, 31
	s_lshl_b32 s10, s11, 7
	s_lshl_b64 s[12:13], s[4:5], 9
	s_lshl_b64 s[14:15], s[4:5], 10
	s_add_u32 s18, s54, s14
	s_addc_u32 s19, s55, s15
	s_ashr_i32 s11, s10, 31
	s_lshl_b64 s[16:17], s[10:11], 11
	v_lshrrev_b32_e32 v12, 3, v0
	v_lshlrev_b32_e32 v6, 3, v0
	s_add_u32 s24, s54, s16
	s_waitcnt lgkmcnt(0)
	v_mov_b32_e32 v3, 0
	v_lshlrev_b32_e32 v2, 10, v12
	s_waitcnt vmcnt(51)
	v_and_b32_e32 v62, 56, v6
	s_addc_u32 s25, s55, s17
	v_lshl_add_u64 v[4:5], s[18:19], 0, v[2:3]
	v_lshlrev_b32_e32 v6, 1, v62
	v_mov_b32_e32 v7, v3
	v_lshlrev_b32_e32 v8, 11, v12
	v_mov_b32_e32 v9, v3
	v_lshl_add_u64 v[4:5], v[4:5], 0, v[6:7]
	v_lshl_add_u64 v[10:11], s[24:25], 0, v[8:9]
	s_mov_b32 s5, 0xd580000
	v_lshl_add_u64 v[6:7], v[10:11], 0, v[6:7]
	v_add_co_u32_e32 v10, vcc, s5, v4
	s_mov_b32 s5, 0xd588000
	s_nop 0
	v_addc_co_u32_e32 v11, vcc, 0, v5, vcc
	v_add_co_u32_e32 v4, vcc, s5, v4
	s_mov_b32 s5, 0xee00000
	s_nop 0
	v_addc_co_u32_e32 v5, vcc, 0, v5, vcc
	s_barrier
	s_mov_b32 m0, s98
	v_lshl_add_u64 v[34:35], v[10:11], 0, v[238:239]
	global_load_lds_dwordx4 v[34:35], off
	s_add_u32 m0, s98, 0x1000
	v_lshl_add_u64 v[38:39], v[4:5], 0, v[238:239]
	global_load_lds_dwordx4 v[38:39], off
	v_add_co_u32_e32 v4, vcc, s5, v6
	s_mov_b32 s5, 0xee10000
	s_nop 0
	v_addc_co_u32_e32 v5, vcc, 0, v7, vcc
	v_add_co_u32_e32 v10, vcc, s5, v6
	s_mov_b32 s5, 0xee20000
	s_nop 0
	v_addc_co_u32_e32 v11, vcc, 0, v7, vcc
	s_add_u32 m0, s98, 0x4000
	v_lshl_add_u64 v[42:43], v[4:5], 0, v[238:239]
	global_load_lds_dwordx4 v[42:43], off
	s_add_u32 m0, s98, 0x5000
	v_lshl_add_u64 v[46:47], v[10:11], 0, v[238:239]
	global_load_lds_dwordx4 v[46:47], off
	v_add_co_u32_e32 v4, vcc, s5, v6
	s_mov_b32 s5, 0xee30000
	s_nop 0
	v_addc_co_u32_e32 v5, vcc, 0, v7, vcc
	v_add_co_u32_e32 v10, vcc, s5, v6
	v_and_b32_e32 v9, 7, v0
	s_nop 0
	v_addc_co_u32_e32 v11, vcc, 0, v7, vcc
	s_add_u32 m0, s98, 0x6000
	v_lshl_add_u64 v[50:51], v[4:5], 0, v[238:239]
	global_load_lds_dwordx4 v[50:51], off
	s_add_u32 m0, s98, 0x7000
	v_lshl_add_u64 v[54:55], v[10:11], 0, v[238:239]
	global_load_lds_dwordx4 v[54:55], off
	v_lshrrev_b32_e32 v4, 4, v0
	v_bitop3_b32 v4, v4, v9, 3 bitop3:0x6c
	v_bfe_u32 v5, v0, 4, 2
	s_mov_b64 s[18:19], 0xee00000
	v_lshlrev_b32_e32 v68, 4, v4
	v_lshlrev_b32_e32 v4, 7, v0
	v_lshrrev_b32_e32 v10, 2, v0
	v_lshl_add_u64 v[64:65], v[6:7], 0, s[18:19]
	v_and_b32_e32 v71, 0x2780, v4
	v_bitop3_b32 v4, v5, v9, 4 bitop3:0x36
	v_lshlrev_b32_e32 v6, 4, v9
	v_lshlrev_b32_e32 v66, 9, v12
	v_lshlrev_b32_e32 v11, 7, v12
	v_xor_b32_e32 v12, v12, v0
	v_and_b32_e32 v63, 32, v10
	v_lshlrev_b32_e32 v72, 4, v4
	v_or3_b32 v4, s14, v2, v6
	v_mov_b32_e32 v5, s15
	s_movk_i32 s11, 0x70
	v_lshlrev_b32_e32 v10, 4, v12
	v_and_or_b32 v67, v0, 15, v63
	s_cmpk_lt_i32 s4, 0x4000
	s_cbranch_scc0 .Ldqw_s
	v_readlane_b32 s34, v237, 3
	v_readlane_b32 s35, v237, 4
	s_mov_b32 s36, s4
	s_branch .Ldqw_j
.Ldqw_s:
	v_readlane_b32 s34, v237, 5
	v_readlane_b32 s35, v237, 6
	s_sub_i32 s36, s4, 0x4000
.Ldqw_j:
	v_add_u32_e32 v100, s36, v67
	v_lshlrev_b32_e32 v100, 12, v100
	v_lshrrev_b32_e32 v102, 1, v0
	v_and_b32_e32 v102, 24, v102
	v_and_b32_e32 v103, 64, v0
	v_or3_b32 v102, v102, v103, s10
	v_lshl_add_u32 v100, v102, 2, v100
	v_add_u32_e32 v101, 0x10000, v100
	v_lshl_add_u64 v[58:59], s[54:55], 0, v[4:5]
	v_or3_b32 v4, s16, v8, v6
	v_mov_b32_e32 v5, s17
	s_mov_b32 s5, 0
	v_and_or_b32 v69, v10, s11, v11
	v_lshlrev_b32_e32 v70, 7, v67
	v_lshl_add_u64 v[60:61], s[54:55], 0, v[4:5]
	s_mov_b64 s[14:15], 0
	s_mov_b32 s11, 0
	v_mov_b32_e32 v2, v3
	v_mov_b32_e32 v4, v3
	v_mov_b32_e32 v5, v3
	v_mov_b32_e32 v22, v3
	v_mov_b32_e32 v23, v3
	v_mov_b32_e32 v24, v3
	v_mov_b32_e32 v25, v3
	v_mov_b32_e32 v26, v3
	v_mov_b32_e32 v27, v3
	v_mov_b32_e32 v28, v3
	v_mov_b32_e32 v29, v3
	v_mov_b32_e32 v30, v3
	v_mov_b32_e32 v31, v3
	v_mov_b32_e32 v32, v3
	v_mov_b32_e32 v33, v3
	v_mov_b32_e32 v14, v3
	v_mov_b32_e32 v15, v3
	v_mov_b32_e32 v16, v3
	v_mov_b32_e32 v17, v3
	v_mov_b32_e32 v18, v3
	v_mov_b32_e32 v19, v3
	v_mov_b32_e32 v20, v3
	v_mov_b32_e32 v21, v3
	v_mov_b32_e32 v10, v3
	v_mov_b32_e32 v11, v3
	v_mov_b32_e32 v12, v3
	v_mov_b32_e32 v13, v3
	v_mov_b32_e32 v6, v3
	v_mov_b32_e32 v7, v3
	v_mov_b32_e32 v8, v3
	v_mov_b32_e32 v9, v3
	s_waitcnt lgkmcnt(0)
	s_add_u32 m0, s98, 0x8000
	v_lshl_add_u64 v[34:35], v[34:35], 0, v[242:243]
	global_load_lds_dwordx4 v[34:35], off
	s_add_u32 m0, s98, 0x9000
	v_lshl_add_u64 v[38:39], v[38:39], 0, v[242:243]
	global_load_lds_dwordx4 v[38:39], off
	s_mov_b32 s100, 0
	s_mov_b32 s101, 0x4000
	s_waitcnt vmcnt(2)
	s_barrier
	s_branch .LBB0_886

.Ldqv_6:
	s_waitcnt vmcnt(8)

.Ldq_6_4:
	s_cmp_lg_u32 s11, 14
	s_cbranch_scc1 .Ldqw_n
	global_load_dwordx4 v[104:107], v100, s[34:35]
	global_load_dwordx4 v[108:111], v100, s[34:35] offset:16
	global_load_dwordx4 v[112:115], v100, s[34:35] offset:128
	global_load_dwordx4 v[116:119], v100, s[34:35] offset:144
	global_load_dwordx4 v[120:123], v101, s[34:35]
	global_load_dwordx4 v[124:127], v101, s[34:35] offset:16
	global_load_dwordx4 v[128:131], v101, s[34:35] offset:128
	global_load_dwordx4 v[132:135], v101, s[34:35] offset:144

.LBB0_900:
	v_readlane_b32 s68, v237, 3
	v_lshrrev_b32_e32 v35, 1, v0
	v_readlane_b32 s69, v237, 4
	v_and_b32_e32 v34, 64, v0
	v_add_u32_e32 v68, s4, v67
	v_and_b32_e32 v35, 24, v35
	s_movk_i32 s5, 0x4000
	v_readlane_b32 s70, v237, 5
	v_readlane_b32 s71, v237, 6
	s_mov_b64 s[12:13], s[68:69]
	v_or3_b32 v70, v35, v34, s10
	v_add_u32_e32 v34, 0xffffc000, v68
	v_ashrrev_i32_e32 v69, 31, v68
	v_cmp_gt_i32_e32 vcc, s5, v68
	s_mov_b64 s[14:15], s[70:71]
	v_mov_b32_e32 v54, s15
	v_cndmask_b32_e32 v35, 0, v69, vcc
	v_cndmask_b32_e32 v34, v34, v68, vcc
	v_mov_b32_e32 v55, s13
	v_mov_b32_e32 v56, s14
	v_mov_b32_e32 v57, s12
	v_ashrrev_i32_e32 v71, 31, v70
	v_cndmask_b32_e32 v37, v54, v55, vcc
	v_cndmask_b32_e32 v36, v56, v57, vcc
	v_lshlrev_b64 v[34:35], 12, v[34:35]
	v_lshl_add_u64 v[34:35], v[36:37], 0, v[34:35]
	v_lshlrev_b64 v[50:51], 2, v[70:71]
	v_lshl_add_u64 v[52:53], v[34:35], 0, v[50:51]
	v_or_b32_e32 v72, 16, v68
	v_add_u32_e32 v52, 0xffffc010, v68
	v_ashrrev_i32_e32 v73, 31, v72
	v_cmp_gt_i32_e32 vcc, s5, v72
	v_lshlrev_b64 v[68:69], 11, v[68:69]
	v_lshl_add_u64 v[68:69], s[54:55], 0, v[68:69]
	v_cndmask_b32_e32 v53, 0, v73, vcc
	v_cndmask_b32_e32 v52, v52, v72, vcc
	v_cndmask_b32_e32 v55, v54, v55, vcc
	v_cndmask_b32_e32 v54, v56, v57, vcc
	v_lshlrev_b64 v[52:53], 12, v[52:53]
	v_lshl_add_u64 v[52:53], v[54:55], 0, v[52:53]
	v_lshl_add_u64 v[74:75], v[52:53], 0, v[50:51]
	v_lshlrev_b64 v[72:73], 11, v[72:73]
	v_lshlrev_b64 v[70:71], 1, v[70:71]
	v_lshl_add_u64 v[72:73], s[54:55], 0, v[72:73]
	v_lshl_add_u64 v[68:69], v[68:69], 0, v[70:71]
	v_lshl_add_u64 v[70:71], v[72:73], 0, v[70:71]
	v_readlane_b32 s72, v237, 7
	v_readlane_b32 s73, v237, 8
	v_readlane_b32 s74, v237, 9
	v_readlane_b32 s75, v237, 10
	v_readlane_b32 s76, v237, 11
	v_readlane_b32 s77, v237, 12
	v_readlane_b32 s78, v237, 13
	v_readlane_b32 s79, v237, 14
	v_readlane_b32 s80, v237, 15
	v_readlane_b32 s81, v237, 16
	v_readlane_b32 s82, v237, 17
	v_readlane_b32 s83, v237, 18
	s_waitcnt vmcnt(0)
	v_mov_b32_e32 v34, v104
	v_mov_b32_e32 v35, v105
	v_mov_b32_e32 v36, v106
	v_mov_b32_e32 v37, v107
	v_mov_b32_e32 v38, v108
	v_mov_b32_e32 v39, v109
	v_mov_b32_e32 v40, v110
	v_mov_b32_e32 v41, v111
	v_mov_b32_e32 v42, v112
	v_mov_b32_e32 v43, v113
	v_mov_b32_e32 v44, v114
	v_mov_b32_e32 v45, v115
	v_mov_b32_e32 v46, v116
	v_mov_b32_e32 v47, v117
	v_mov_b32_e32 v48, v118
	v_mov_b32_e32 v49, v119
	v_mov_b32_e32 v50, v120
	v_mov_b32_e32 v51, v121
	v_mov_b32_e32 v52, v122
	v_mov_b32_e32 v53, v123
	v_mov_b32_e32 v54, v124
	v_mov_b32_e32 v55, v125
	v_mov_b32_e32 v56, v126
	v_mov_b32_e32 v57, v127
	v_mov_b32_e32 v58, v128
	v_mov_b32_e32 v59, v129
	v_mov_b32_e32 v60, v130
	v_mov_b32_e32 v61, v131
	v_mov_b32_e32 v64, v132
	v_mov_b32_e32 v65, v133
	v_mov_b32_e32 v66, v134
	v_mov_b32_e32 v67, v135
	v_pk_add_f32 v[2:3], v[2:3], v[34:35]
	s_waitcnt vmcnt(6)
	v_pk_add_f32 v[34:35], v[22:23], v[38:39]
	v_pk_add_f32 v[4:5], v[4:5], v[36:37]
	v_pk_add_f32 v[36:37], v[24:25], v[40:41]
	s_waitcnt vmcnt(5)
	v_pk_add_f32 v[38:39], v[26:27], v[42:43]
	v_pk_add_f32 v[28:29], v[28:29], v[44:45]
	s_waitcnt vmcnt(4)
	v_pk_add_f32 v[30:31], v[30:31], v[46:47]
	v_pk_mul_f32 v[40:41], v[2:3], v[2:3]
	v_cvt_pk_bf16_f32 v24, v34, v35
	v_pk_mul_f32 v[34:35], v[34:35], v[34:35]
	v_cvt_pk_bf16_f32 v23, v4, v5
	v_pk_mul_f32 v[42:43], v[4:5], v[4:5]
	v_cvt_pk_bf16_f32 v25, v36, v37
	v_pk_mul_f32 v[36:37], v[36:37], v[36:37]
	v_cvt_pk_bf16_f32 v26, v38, v39
	v_cvt_pk_bf16_f32 v27, v28, v29
	v_pk_mul_f32 v[38:39], v[38:39], v[38:39]
	v_pk_mul_f32 v[44:45], v[28:29], v[28:29]
	v_cvt_pk_bf16_f32 v28, v30, v31
	v_pk_mul_f32 v[30:31], v[30:31], v[30:31]
	s_waitcnt vmcnt(3)
	v_pk_add_f32 v[4:5], v[16:17], v[52:53]
	s_waitcnt vmcnt(2)
	v_pk_add_f32 v[16:17], v[20:21], v[56:57]
	v_add_f32_e32 v21, v34, v35
	v_add_f32_e32 v34, v40, v41
	v_pk_add_f32 v[32:33], v[32:33], v[48:49]
	v_add_f32_e32 v35, v38, v39
	v_add_f32_e32 v30, v30, v31
	v_add_f32_e32 v21, v21, v36
	v_add_f32_e32 v31, v34, v42
	v_cvt_pk_bf16_f32 v29, v32, v33
	v_pk_mul_f32 v[32:33], v[32:33], v[32:33]
	v_add_f32_e32 v34, v35, v44
	v_add_f32_e32 v21, v21, v37
	v_add_f32_e32 v31, v31, v43
	v_cvt_pk_bf16_f32 v22, v2, v3
	v_pk_add_f32 v[2:3], v[14:15], v[50:51]
	v_add_f32_e32 v30, v30, v32
	v_add_f32_e32 v32, v34, v45
	v_add_f32_e32 v21, v31, v21
	v_pk_add_f32 v[14:15], v[18:19], v[54:55]
	v_cvt_pk_bf16_f32 v18, v2, v3
	v_add_f32_e32 v30, v30, v33
	v_add_f32_e32 v21, v21, v32
	v_cvt_pk_bf16_f32 v19, v4, v5
	v_cvt_pk_bf16_f32 v20, v14, v15
	v_add_f32_e32 v34, v21, v30
	v_cvt_pk_bf16_f32 v21, v16, v17
	global_store_dwordx4 v[68:69], v[22:25], off
	global_store_dwordx4 v[68:69], v[26:29], off offset:64
	global_store_dwordx4 v[70:71], v[18:21], off
	s_waitcnt vmcnt(4)
	v_pk_add_f32 v[10:11], v[10:11], v[58:59]
	v_pk_add_f32 v[12:13], v[12:13], v[60:61]
	v_mbcnt_lo_u32_b32 v18, -1, 0
	v_mbcnt_hi_u32_b32 v18, -1, v18
	v_and_b32_e32 v20, 64, v18
	v_xor_b32_e32 v19, 16, v18
	v_add_u32_e32 v21, 64, v20
	v_cmp_lt_i32_e32 vcc, v19, v21
	v_xor_b32_e32 v22, 32, v18
	s_waitcnt vmcnt(3)
	v_pk_add_f32 v[6:7], v[6:7], v[64:65]
	v_cndmask_b32_e32 v19, v18, v19, vcc
	v_lshlrev_b32_e32 v20, 2, v19
	ds_bpermute_b32 v19, v20, v34
	v_cmp_lt_i32_e32 vcc, v22, v21
	v_pk_add_f32 v[8:9], v[8:9], v[66:67]
	v_cvt_pk_bf16_f32 v30, v10, v11
	v_cndmask_b32_e32 v18, v18, v22, vcc
	v_lshlrev_b32_e32 v21, 2, v18
	s_waitcnt lgkmcnt(0)
	v_add_f32_e32 v22, v34, v19
	ds_bpermute_b32 v23, v21, v22
	v_add3_u32 v18, v63, v1, s4
	v_cvt_pk_bf16_f32 v31, v12, v13
	v_cvt_pk_bf16_f32 v32, v6, v7
	v_cvt_pk_bf16_f32 v33, v8, v9
	v_cmp_gt_u32_e32 vcc, 16, v1
	v_ashrrev_i32_e32 v19, 31, v18
	global_store_dwordx4 v[70:71], v[30:33], off offset:64
	s_and_saveexec_b64 s[4:5], vcc
	s_cbranch_execz .LBB0_902
	s_waitcnt lgkmcnt(0)
	v_add_f32_e32 v24, v22, v23
	v_lshl_add_u64 v[22:23], v[18:19], 2, s[0:1]
	global_atomic_add_f32 v[22:23], v24, off

.LBB0_939:
	s_xor_b64 s[4:5], s[2:3], -1
	s_cmpk_lt_i32 s16, 0x440
	s_cselect_b64 s[2:3], -1, 0
	s_and_b64 s[2:3], s[8:9], s[2:3]
	s_andn2_b64 vcc, exec, s[2:3]
	s_cbranch_vccnz .LBB0_950
	v_lshrrev_b32_e32 v4, 3, v0
	v_xor_b32_e32 v6, v4, v0
	v_lshlrev_b32_e32 v5, 7, v4
	v_lshlrev_b32_e32 v6, 4, v6
	s_movk_i32 s2, 0x70
	v_lshrrev_b32_e32 v2, 4, v0
	v_and_or_b32 v110, v6, s2, v5
	v_and_b32_e32 v6, 7, v0
	v_bitop3_b32 v2, v2, v6, 3 bitop3:0x6c
	s_waitcnt lgkmcnt(0)
	v_bfe_u32 v3, v0, 4, 2
	v_lshlrev_b32_e32 v111, 4, v2
	v_lshlrev_b32_e32 v2, 7, v0
	v_and_b32_e32 v114, 0x2780, v2
	v_bitop3_b32 v2, v3, v6, 4 bitop3:0x36
	v_readlane_b32 s6, v237, 52
	v_lshrrev_b32_e32 v5, 1, v0
	v_lshlrev_b32_e32 v115, 4, v2
	v_and_b32_e32 v2, 64, v0
	v_lshlrev_b32_e32 v98, 9, v4
	v_mov_b32_e32 v99, 0
	v_readlane_b32 s7, v237, 53
	v_lshlrev_b32_e32 v4, 4, v0
	v_and_or_b32 v112, v5, 64, v174
	v_and_or_b32 v116, v5, 24, v2
	v_lshl_add_u64 v[2:3], s[6:7], 0, v[98:99]
	v_and_b32_e32 v4, 0x70, v4
	v_mov_b32_e32 v5, v99
	v_lshl_add_u64 v[100:101], v[2:3], 0, v[4:5]
	v_lshl_add_u64 v[2:3], s[54:55], 0, v[98:99]
	v_lshl_add_u64 v[2:3], v[2:3], 0, v[4:5]
	s_mov_b64 s[6:7], 0xf200000
	v_lshl_add_u64 v[102:103], v[2:3], 0, s[6:7]
	v_lshlrev_b32_e32 v2, 6, v0
	v_lshlrev_b32_e32 v3, 4, v6
	s_movk_i32 s6, 0x3e00
	s_add_u32 s2, s54, 0xaa00000
	v_and_or_b32 v98, v2, s6, v3
	v_lshlrev_b32_e32 v113, 7, v112
	s_addc_u32 s3, s55, 0
	v_lshl_add_u64 v[104:105], s[54:55], 0, v[98:99]
	s_lshl_b32 s18, s16, 4
	s_lshl_b32 s19, s17, 4
	s_lshl_b32 s20, s16, 7
	s_lshl_b32 s21, s17, 7
	s_mov_b32 s7, 0
	s_movk_i32 s22, 0x4000
	s_mov_b32 s23, 0x8000
	s_mov_b32 s24, 0xc000
	s_mov_b32 s38, 0
	s_lshr_b32 s40, s17, 3
	s_lshl_b32 s40, s40, 16
	s_sub_u32 s40, s40, 0x200
	s_mov_b32 s41, 0
	s_mov_b32 s42, 0xfffffe00
	s_mov_b32 s43, -1
	s_branch .LBB0_942

.LBB0_942:
	s_add_i32 s39, s16, s17
	s_cmpk_lt_i32 s39, 0x440
	s_cselect_b32 s37, 1, 0
	s_cmp_eq_u32 s38, 1
	s_cbranch_scc1 .Ldqp_dry
	s_lshl_b32 s6, s20, 9
	s_and_b32 s6, s6, 0x70000
	v_lshl_add_u64 v[106:107], v[104:105], 0, s[6:7]
	s_lshl_b32 s6, s16, 4
	s_lshl_b32 s9, s16, 7
	s_and_b32 s8, s6, 0xffffff80
	s_and_b32 s25, s9, 0x380
	s_ashr_i32 s9, s8, 31
	s_lshl_b64 s[10:11], s[8:9], 9
	v_lshl_add_u64 v[2:3], v[100:101], 0, s[10:11]
	v_add_co_u32_e32 v6, vcc, s22, v2
	s_lshl_b32 s6, s25, 9
	s_nop 0
	v_addc_co_u32_e32 v7, vcc, 0, v3, vcc
	v_add_co_u32_e32 v8, vcc, s23, v2
	s_nop 1
	v_addc_co_u32_e32 v9, vcc, 0, v3, vcc
	s_barrier
	s_add_u32 m0, s98, 0x1000
	v_lshl_add_u64 v[10:11], v[6:7], 0, v[238:239]
	global_load_lds_dwordx4 v[10:11], off
	s_add_u32 m0, s98, 0x2000
	v_lshl_add_u64 v[26:27], v[8:9], 0, v[238:239]
	global_load_lds_dwordx4 v[26:27], off
	v_add_co_u32_e32 v6, vcc, s24, v2
	v_lshl_add_u64 v[4:5], v[102:103], 0, s[6:7]
	s_nop 0
	v_addc_co_u32_e32 v7, vcc, 0, v3, vcc
	s_mov_b32 m0, s98
	v_lshl_add_u64 v[18:19], v[2:3], 0, v[238:239]
	global_load_lds_dwordx4 v[18:19], off
	s_add_u32 m0, s98, 0x4000
	v_lshl_add_u64 v[42:43], v[4:5], 0, v[238:239]
	global_load_lds_dwordx4 v[42:43], off
	v_add_co_u32_e32 v2, vcc, s22, v4
	s_and_b32 s12, s18, 0xffffff80
	s_nop 0
	v_addc_co_u32_e32 v3, vcc, 0, v5, vcc
	s_add_u32 m0, s98, 0x3000
	v_lshl_add_u64 v[38:39], v[6:7], 0, v[238:239]
	global_load_lds_dwordx4 v[38:39], off
	s_add_u32 m0, s98, 0x5000
	v_lshl_add_u64 v[46:47], v[2:3], 0, v[238:239]
	global_load_lds_dwordx4 v[46:47], off
	v_add_co_u32_e32 v2, vcc, s23, v4
	s_ashr_i32 s13, s12, 31
	s_nop 0
	v_addc_co_u32_e32 v3, vcc, 0, v5, vcc
	v_add_co_u32_e32 v4, vcc, 0xc000, v4
	s_lshl_b64 s[12:13], s[12:13], 9
	s_nop 0
	v_addc_co_u32_e32 v5, vcc, 0, v5, vcc
	s_add_u32 m0, s98, 0x6000
	v_lshl_add_u64 v[58:59], v[2:3], 0, v[238:239]
	global_load_lds_dwordx4 v[58:59], off
	s_add_u32 m0, s98, 0x7000
	v_lshl_add_u64 v[62:63], v[4:5], 0, v[238:239]
	global_load_lds_dwordx4 v[62:63], off
	s_mov_b64 s[10:11], 0
	s_mov_b32 s9, 0
	s_mov_b32 s6, 0
	s_mov_b32 s39, 0
	v_mov_b32_e32 v2, 0
	v_mov_b32_e32 v3, v99
	v_mov_b32_e32 v4, v99
	v_mov_b32_e32 v5, v99
	v_mov_b32_e32 v6, 0
	v_mov_b32_e32 v7, v99
	v_mov_b32_e32 v8, v99
	v_mov_b32_e32 v9, v99
	v_mov_b32_e32 v14, 0
	v_mov_b32_e32 v15, v99
	v_mov_b32_e32 v16, v99
	v_mov_b32_e32 v17, v99
	v_mov_b32_e32 v22, 0
	v_mov_b32_e32 v23, v99
	v_mov_b32_e32 v24, v99
	v_mov_b32_e32 v25, v99
	v_mov_b32_e32 v30, 0
	v_mov_b32_e32 v31, v99
	v_mov_b32_e32 v32, v99
	v_mov_b32_e32 v33, v99
	v_mov_b32_e32 v34, 0
	v_mov_b32_e32 v35, v99
	v_lshl_add_u64 v[108:109], v[104:105], 0, s[12:13]
	v_mov_b32_e32 v36, v99
	v_mov_b32_e32 v37, v99
	v_mov_b32_e32 v50, 0
	v_mov_b32_e32 v51, v99
	v_mov_b32_e32 v52, v99
	v_mov_b32_e32 v53, v99
	v_mov_b32_e32 v54, 0
	v_mov_b32_e32 v55, v99
	v_mov_b32_e32 v56, v99
	v_mov_b32_e32 v57, v99
	v_mov_b32_e32 v66, 0
	v_mov_b32_e32 v67, v99
	v_mov_b32_e32 v68, v99
	v_mov_b32_e32 v69, v99
	v_mov_b32_e32 v70, 0
	v_mov_b32_e32 v71, v99
	v_mov_b32_e32 v72, v99
	v_mov_b32_e32 v73, v99
	v_mov_b32_e32 v74, 0
	v_mov_b32_e32 v75, v99
	v_mov_b32_e32 v76, v99
	v_mov_b32_e32 v77, v99
	v_mov_b32_e32 v78, 0
	v_mov_b32_e32 v79, v99
	v_mov_b32_e32 v80, v99
	v_mov_b32_e32 v81, v99
	v_mov_b32_e32 v82, 0
	v_mov_b32_e32 v83, v99
	v_mov_b32_e32 v84, v99
	v_mov_b32_e32 v85, v99
	v_mov_b32_e32 v86, 0
	v_mov_b32_e32 v87, v99
	v_mov_b32_e32 v88, v99
	v_mov_b32_e32 v89, v99
	v_mov_b32_e32 v90, 0
	v_mov_b32_e32 v91, v99
	v_mov_b32_e32 v92, v99
	v_mov_b32_e32 v93, v99
	v_mov_b32_e32 v94, 0
	v_mov_b32_e32 v95, v99
	v_mov_b32_e32 v96, v99
	v_mov_b32_e32 v97, v99
	s_waitcnt lgkmcnt(0)
	s_add_u32 m0, s98, 0x8000
	v_lshl_add_u64 v[18:19], v[18:19], 0, v[242:243]
	global_load_lds_dwordx4 v[18:19], off
	s_add_u32 m0, s98, 0x9000
	v_lshl_add_u64 v[10:11], v[10:11], 0, v[242:243]
	global_load_lds_dwordx4 v[10:11], off
	s_add_u32 m0, s98, 0xa000
	v_lshl_add_u64 v[26:27], v[26:27], 0, v[242:243]
	global_load_lds_dwordx4 v[26:27], off
	s_add_u32 m0, s98, 0xb000
	v_lshl_add_u64 v[38:39], v[38:39], 0, v[242:243]
	global_load_lds_dwordx4 v[38:39], off
	s_mov_b32 s100, 0
	s_mov_b32 s101, 0x4000
	s_waitcnt vmcnt(4)
	s_barrier
	s_branch .LBB0_944
.Ldqp_dry:
	s_mov_b32 s39, 0
	s_lshl_b32 s6, s20, 9
	s_and_b32 s6, s6, 0x70000
	v_lshl_add_u64 v[106:107], v[104:105], 0, s[6:7]
	s_lshl_b32 s6, s16, 4
	s_lshl_b32 s9, s16, 7
	s_and_b32 s8, s6, 0xffffff80
	s_and_b32 s25, s9, 0x380
	s_ashr_i32 s9, s8, 31
	s_lshl_b64 s[10:11], s[8:9], 9
	v_lshl_add_u64 v[2:3], v[100:101], 0, s[10:11]
	v_add_co_u32_e32 v6, vcc, s22, v2
	s_lshl_b32 s6, s25, 9
	s_nop 0
	v_addc_co_u32_e32 v7, vcc, 0, v3, vcc
	v_add_co_u32_e32 v8, vcc, s23, v2
	s_nop 1
	v_addc_co_u32_e32 v9, vcc, 0, v3, vcc
	v_lshl_add_u64 v[10:11], v[6:7], 0, v[238:239]
	v_lshl_add_u64 v[26:27], v[8:9], 0, v[238:239]
	v_add_co_u32_e32 v6, vcc, s24, v2
	v_lshl_add_u64 v[4:5], v[102:103], 0, s[6:7]
	s_nop 0
	v_addc_co_u32_e32 v7, vcc, 0, v3, vcc
	v_lshl_add_u64 v[18:19], v[2:3], 0, v[238:239]
	v_lshl_add_u64 v[42:43], v[4:5], 0, v[238:239]
	v_add_co_u32_e32 v2, vcc, s22, v4
	s_and_b32 s12, s18, 0xffffff80
	s_nop 0
	v_addc_co_u32_e32 v3, vcc, 0, v5, vcc
	v_lshl_add_u64 v[38:39], v[6:7], 0, v[238:239]
	v_lshl_add_u64 v[46:47], v[2:3], 0, v[238:239]
	v_add_co_u32_e32 v2, vcc, s23, v4
	s_ashr_i32 s13, s12, 31
	s_nop 0
	v_addc_co_u32_e32 v3, vcc, 0, v5, vcc
	v_add_co_u32_e32 v4, vcc, 0xc000, v4
	s_lshl_b64 s[12:13], s[12:13], 9
	s_nop 0
	v_addc_co_u32_e32 v5, vcc, 0, v5, vcc
	v_lshl_add_u64 v[58:59], v[2:3], 0, v[238:239]
	v_lshl_add_u64 v[62:63], v[4:5], 0, v[238:239]
	s_mov_b64 s[10:11], 0
	s_mov_b32 s9, 0
	s_mov_b32 s6, 0
	v_mov_b32_e32 v2, 0
	v_mov_b32_e32 v3, v99
	v_mov_b32_e32 v4, v99
	v_mov_b32_e32 v5, v99
	v_mov_b32_e32 v6, 0
	v_mov_b32_e32 v7, v99
	v_mov_b32_e32 v8, v99
	v_mov_b32_e32 v9, v99
	v_mov_b32_e32 v14, 0
	v_mov_b32_e32 v15, v99
	v_mov_b32_e32 v16, v99
	v_mov_b32_e32 v17, v99
	v_mov_b32_e32 v22, 0
	v_mov_b32_e32 v23, v99
	v_mov_b32_e32 v24, v99
	v_mov_b32_e32 v25, v99
	v_mov_b32_e32 v30, 0
	v_mov_b32_e32 v31, v99
	v_mov_b32_e32 v32, v99
	v_mov_b32_e32 v33, v99
	v_mov_b32_e32 v34, 0
	v_mov_b32_e32 v35, v99
	v_lshl_add_u64 v[108:109], v[104:105], 0, s[12:13]
	v_mov_b32_e32 v36, v99
	v_mov_b32_e32 v37, v99
	v_mov_b32_e32 v50, 0
	v_mov_b32_e32 v51, v99
	v_mov_b32_e32 v52, v99
	v_mov_b32_e32 v53, v99
	v_mov_b32_e32 v54, 0
	v_mov_b32_e32 v55, v99
	v_mov_b32_e32 v56, v99
	v_mov_b32_e32 v57, v99
	v_mov_b32_e32 v66, 0
	v_mov_b32_e32 v67, v99
	v_mov_b32_e32 v68, v99
	v_mov_b32_e32 v69, v99
	v_mov_b32_e32 v70, 0
	v_mov_b32_e32 v71, v99
	v_mov_b32_e32 v72, v99
	v_mov_b32_e32 v73, v99
	v_mov_b32_e32 v74, 0
	v_mov_b32_e32 v75, v99
	v_mov_b32_e32 v76, v99
	v_mov_b32_e32 v77, v99
	v_mov_b32_e32 v78, 0
	v_mov_b32_e32 v79, v99
	v_mov_b32_e32 v80, v99
	v_mov_b32_e32 v81, v99
	v_mov_b32_e32 v82, 0
	v_mov_b32_e32 v83, v99
	v_mov_b32_e32 v84, v99
	v_mov_b32_e32 v85, v99
	v_mov_b32_e32 v86, 0
	v_mov_b32_e32 v87, v99
	v_mov_b32_e32 v88, v99
	v_mov_b32_e32 v89, v99
	v_mov_b32_e32 v90, 0
	v_mov_b32_e32 v91, v99
	v_mov_b32_e32 v92, v99
	v_mov_b32_e32 v93, v99
	v_mov_b32_e32 v94, 0
	v_mov_b32_e32 v95, v99
	v_mov_b32_e32 v96, v99
	v_mov_b32_e32 v97, v99
	s_waitcnt lgkmcnt(0)
	v_lshl_add_u64 v[18:19], v[18:19], 0, v[242:243]
	v_lshl_add_u64 v[10:11], v[10:11], 0, v[242:243]
	v_lshl_add_u64 v[26:27], v[26:27], 0, v[242:243]
	v_lshl_add_u64 v[38:39], v[38:39], 0, v[242:243]
	s_branch .LBB0_944
.LBB0_943:
	s_add_u32 s10, s10, 0x80
	s_addc_u32 s11, s11, 0
	s_add_i32 s6, s6, 1
	s_cmp_eq_u32 s37, 1
	s_cselect_b32 s39, 0, s6
	s_mov_b32 s38, s37
	s_cbranch_scc0 .Ldqp_nj
	s_cmp_eq_u32 s6, 2
	s_cbranch_scc0 .Ldqp_j3
	v_lshl_add_u64 v[18:19], s[40:41], 0, v[18:19]
	v_lshl_add_u64 v[10:11], s[40:41], 0, v[10:11]
	v_lshl_add_u64 v[26:27], s[40:41], 0, v[26:27]
	v_lshl_add_u64 v[38:39], s[40:41], 0, v[38:39]
	s_branch .Ldqp_nj
.Ldqp_j3:
	s_cmp_eq_u32 s6, 3
	s_cbranch_scc0 .Ldqp_nj
	v_lshl_add_u64 v[42:43], s[42:43], 0, v[42:43]
	v_lshl_add_u64 v[46:47], s[42:43], 0, v[46:47]
	v_lshl_add_u64 v[58:59], s[42:43], 0, v[58:59]
	v_lshl_add_u64 v[62:63], s[42:43], 0, v[62:63]

.Ldqs_10:
	s_cmp_gt_u32 s39, 2
	s_cbranch_scc1 .Ldqv_10
	s_waitcnt vmcnt(4)
	s_branch .Ldqx_10

.LBB0_944:
	s_cmp_gt_u32 s39, 2
	s_cselect_b64 s[12:13], -1, 0
	s_and_b64 vcc, exec, s[12:13]
	s_cbranch_vccnz .LBB0_946

.Ldq_10_3:
	v_add_u32_e32 v98, v98, v113
	s_mov_b64 s[14:15], -1
	v_mfma_f32_16x16x32_bf16 v[50:53], v[122:125], v[126:129], v[50:53]
	v_mfma_f32_16x16x32_bf16 v[34:37], v[134:137], v[126:129], v[34:37]
	s_cmp_gt_u32 s39, 1
	s_cbranch_scc1 .Ldq_10_4
	s_add_u32 s99, s100, 0x10000
	s_cmp_lt_u32 s99, 0x14000
	s_cbranch_scc1 .Ldqw_10_4
	s_sub_u32 s99, s99, 0x14000

.Ldq_10_4:
	v_mfma_f32_16x16x32_bf16 v[30:33], v[138:141], v[126:129], v[30:33]
	s_waitcnt lgkmcnt(0)
	v_mfma_f32_16x16x32_bf16 v[22:25], v[118:121], v[130:133], v[22:25]
	s_cmp_gt_u32 s39, 1
	s_cbranch_scc1 .Ldq_10_5
	s_add_u32 m0, s99, 0x1000
	v_lshl_add_u64 v[10:11], v[10:11], 0, v[242:243]
	global_load_lds_dwordx4 v[10:11], off
.Ldq_10_5:
	ds_read_b128 v[118:121], v117
	v_mfma_f32_16x16x32_bf16 v[14:17], v[122:125], v[130:133], v[14:17]
	v_mfma_f32_16x16x32_bf16 v[6:9], v[134:137], v[130:133], v[6:9]
	s_cmp_gt_u32 s39, 1
	s_cbranch_scc1 .Ldq_10_6
	s_add_u32 m0, s99, 0x2000
	v_lshl_add_u64 v[26:27], v[26:27], 0, v[242:243]
	global_load_lds_dwordx4 v[26:27], off
.Ldq_10_6:
	v_mfma_f32_16x16x32_bf16 v[2:5], v[138:141], v[130:133], v[2:5]
	ds_read_b128 v[122:125], v117 offset:2048
	ds_read_b128 v[126:129], v98
	ds_read_b128 v[130:133], v98 offset:2048
	ds_read_b128 v[134:137], v117 offset:4096
	ds_read_b128 v[138:141], v117 offset:6144
	s_waitcnt lgkmcnt(3)
	v_mfma_f32_16x16x32_bf16 v[94:97], v[118:121], v[126:129], v[94:97]
	s_cmp_gt_u32 s39, 1
	s_cbranch_scc1 .Ldq_10_7
	s_add_u32 m0, s99, 0x3000
	v_lshl_add_u64 v[38:39], v[38:39], 0, v[242:243]
	global_load_lds_dwordx4 v[38:39], off
